# attention work queue: next unit's index fetched at the start of the current unit's epilogue (atomic latency off the loop top)
# baseline (speedup 1.0000x reference)
; #define LAS3 __attribute__((address_space(3)))
; #define LAS __attribute__((address_space(3)))
; __device__ __forceinline__ void fox_unit(int b, int hh, int qb, const bf16_t* Q, const bf16_t* __restrict__ K, const bf16_t* __restrict__ V, bf16_t* O, ...
;     ...
;     const short one = (short)0x3F80;
;     const bf16x8 onesA = (bf16x8){one, one, one, one, one, one, one, one};
;     const bf16x8 qones = hi ? (bf16x8){0, 0, 0, 0, 0, 0, 0, 0} : (bf16x8){one, one, one, 0, 0, 0, 0, 0};
;     f32x16 o0, o1, lacc, cinit;
; #pragma unroll
;     for (int r = 0; r < 16; ++r) { o0[r] = 0.f; o1[r] = 0.f; lacc[r] = 0.f; cinit[r] = ft2 - fminf(zq, 60.0f); }
;     const float mref = fminf(zq, 60.0f);
;     volatile LAS3 unsigned* flags = (volatile LAS3 unsigned*)(shm + L_FLAG);
;     const LAS3 unsigned char* kp0 = shm + L_K + hi * 1024 + r32 * 16;
;     const LAS3 unsigned char* vp0 = shm + L_V + ((lane >> 4) & 1) * 32 + (lane & 3) * 8 + (4 * hi + ((lane & 15) >> 2)) * 64;
;     const LAS3 unsigned char* fp0 = shm + L_F + r32 * 16;
; __global__ void __launch_bounds__(NWAVES * 64, 2) fwd_megakernel(Args args) {
;     ...
;         volatile LAS unsigned* qw = (volatile LAS unsigned*)(lds + att::L_FLAG + 64);
;         for (;;) {
;             if (tid == 0) qw[0] = atomicAdd(CTL, 1u);
;             __syncthreads();
;             const unsigned idx = qw[0];
;             if (idx >= 2048u) break;
;             if (idx < 1024u) { const int qb = 31 - (int)(idx >> 5), bh = (int)(idx & 31);
.LBB0_355:
	v_writelane_b32 v249, s74, 25
	s_nop 1
	v_writelane_b32 v249, s75, 26
	v_writelane_b32 v249, s90, 27
	v_writelane_b32 v249, s59, 28
	v_writelane_b32 v249, s88, 29
	s_nop 1
	v_writelane_b32 v249, s89, 30
	v_writelane_b32 v249, s68, 31
	s_nop 1
	v_writelane_b32 v249, s69, 32
	v_writelane_b32 v249, s70, 33
	v_writelane_b32 v249, s71, 34
	v_writelane_b32 v249, s64, 35
	s_nop 1
	v_writelane_b32 v249, s65, 36
	v_writelane_b32 v249, s62, 37
	s_nop 1
	v_writelane_b32 v249, s63, 38
	v_writelane_b32 v249, s60, 39
	s_nop 1
	v_writelane_b32 v249, s61, 40
	s_or_b64 exec, exec, s[0:1]
	s_add_u32 s0, s66, 0x1c00000
	s_addc_u32 s1, s67, 0
	s_add_u32 s88, s66, 0xb000000
	s_addc_u32 s95, s67, 0
	v_writelane_b32 v249, s0, 41
	s_add_u32 s96, s66, 0xf000000
	s_addc_u32 s97, s67, 0
	v_writelane_b32 v249, s1, 42
	s_add_u32 s93, s66, 0x13000000
	v_writelane_b32 v249, s66, 43
	v_cmp_eq_u32_e64 s[0:1], 0, v180
	s_addc_u32 s94, s67, 0
	v_writelane_b32 v249, s67, 44
	v_writelane_b32 v249, s0, 45
	v_lshlrev_b32_e32 v7, 1, v178
	v_and_b32_e32 v8, 0xc0, v130
	v_writelane_b32 v249, s1, 46
	v_cmp_ne_u32_e64 s[0:1], 0, v180
	v_and_b32_e32 v4, 24, v181
	v_and_b32_e32 v7, 32, v7
	v_writelane_b32 v249, s0, 47
	v_lshl_or_b32 v8, v185, 8, v8
	v_or3_b32 v8, v8, v7, v4
	v_writelane_b32 v249, s1, 48
	s_add_i32 s1, 0, 0x10c00
	v_writelane_b32 v249, s1, 49
	s_add_i32 s1, 0, 0x10800
	v_writelane_b32 v249, s1, 50
	s_add_i32 s1, 0, 0x1f004
	v_writelane_b32 v249, s1, 51
	s_add_i32 s1, 0, 0x1f008
	s_add_i32 s0, 0, 0x1f040
	v_writelane_b32 v249, s1, 52
	v_add_u32_e32 v139, 0, v8
	v_lshlrev_b32_e32 v8, 2, v185
	v_lshrrev_b32_e32 v9, 2, v178
	v_writelane_b32 v249, s0, 53
	v_and_or_b32 v9, v9, 3, v8
	v_writelane_b32 v249, s93, 54
	v_add_u32_e32 v7, 0, v7
	v_lshlrev_b32_e32 v9, 6, v9
	v_writelane_b32 v249, s94, 55
	v_lshlrev_b32_e32 v5, 10, v185
	v_lshlrev_b32_e32 v6, 4, v182
	v_add3_u32 v165, v7, v4, v9
	v_mov_b32_e32 v7, 0x3f80
	v_cmp_gt_u32_e64 s[8:9], 32, v180
	v_writelane_b32 v249, s88, 56
	s_waitcnt lgkmcnt(0)
	v_lshlrev_b32_e32 v2, 10, v180
	v_mov_b32_e32 v3, 0
	v_add3_u32 v137, 0, v5, v6
	v_lshlrev_b32_e32 v140, 10, v183
	s_add_i32 s92, 0, 0x10000
	v_cndmask_b32_e64 v115, 0, v7, s[8:9]
	v_mov_b32_e32 v7, 0x3f803f80
	v_sub_u32_e32 v167, v8, v182
	v_or_b32_e32 v5, v5, v6
	v_writelane_b32 v249, s95, 57
	v_lshrrev_b32_e32 v135, 2, v180
	v_lshlrev_b32_e32 v134, 10, v182
	v_lshlrev_b32_e32 v136, 3, v185
	s_mov_b32 s81, 0
	v_mul_u32_u24_e32 v162, 0x90, v182
	v_lshlrev_b32_e32 v163, 4, v184
	v_lshlrev_b32_e32 v138, 3, v184
	v_mul_u32_u24_e32 v164, 0x90, v183
	v_mov_b32_e32 v141, v3
	v_or_b32_e32 v142, 0x2000, v140
	v_mov_b32_e32 v143, v3
	v_or_b32_e32 v144, 0x4000, v140
	v_mov_b32_e32 v145, v3
	v_or_b32_e32 v146, 0x6000, v140
	v_mov_b32_e32 v147, v3
	v_lshlrev_b32_e32 v148, 11, v180
	v_mov_b32_e32 v149, v3
	v_lshlrev_b32_e32 v150, 7, v180
	v_mov_b32_e32 v151, v3
	v_add_u32_e32 v166, s92, v6
	s_mov_b32 s76, 0x3f803f80
	v_cndmask_b32_e64 v114, 0, v7, s[8:9]
	v_mov_b32_e32 v116, v3
	v_mov_b32_e32 v117, v3
	v_add_u32_e32 v168, 0xffffe100, v167
	v_add_u32_e32 v169, 0, v5
	v_add_u32_e32 v170, 0xffffe0c0, v167
	v_add_u32_e32 v171, 0xffffe080, v167
	v_lshlrev_b32_e32 v152, 1, v2
	v_mov_b32_e32 v172, 0x260
	s_add_i32 s89, 0, 0x1f00c
	s_add_i32 s90, 0, 0x1f014
	s_add_i32 s91, 0, 0x1f018
	s_add_i32 s4, 0, 0x1f01c
	v_mov_b32_e32 v173, s0
	v_lshlrev_b32_e32 v154, 1, v4
	v_mov_b32_e32 v174, 0xff800000
	v_writelane_b32 v249, s96, 58
	s_barrier
	v_writelane_b32 v249, s97, 59
	s_mov_b64 s[98:99], exec
	v_readlane_b32 s100, v249, 10
	v_readlane_b32 s101, v249, 11
	s_nop 0
	s_and_b64 exec, s[98:99], s[100:101]
	s_cbranch_execz .Lqpf_skip0
	v_readlane_b32 s100, v249, 43
	v_readlane_b32 s101, v249, 44
	v_mov_b32_e32 v187, 1
	s_nop 3
	global_atomic_add v187, v3, v187, s[100:101] sc0
.Lqpf_skip0:
	s_mov_b64 exec, s[98:99]
	s_branch .LBB0_359

; __global__ void __launch_bounds__(NWAVES * 64, 2) fwd_megakernel(Args args) {
;     ...
;         for (;;) {
;             if (tid == 0) qw[0] = atomicAdd(CTL, 1u);
;             __syncthreads();
;             const unsigned idx = qw[0];
.LBB0_359:
	s_mov_b64 s[0:1], exec
	v_readlane_b32 s2, v249, 10
	v_readlane_b32 s3, v249, 11
	s_and_b64 s[2:3], s[0:1], s[2:3]
	s_mov_b64 exec, s[2:3]
	s_cbranch_execz .LBB0_363
	s_mov_b64 s[10:11], exec
	v_mbcnt_lo_u32_b32 v2, s10, 0
	v_mbcnt_hi_u32_b32 v2, s11, v2
	v_cmp_eq_u32_e32 vcc, 0, v2
	s_and_saveexec_b64 s[6:7], vcc
	s_cbranch_execz .LBB0_362
	s_waitcnt vmcnt(0)
	v_mov_b32_e32 v4, v187

; #define ATT_WAIT_BAR() asm volatile("s_waitcnt vmcnt(0) lgkmcnt(0)\n\ts_barrier" ::: "memory")
; __device__ __forceinline__ void sb_unit(int b, int hh, int qb, const bf16_t* Q, const bf16_t* __restrict__ K, const bf16_t* __restrict__ V, bf16_t* O, float* SS, LAS3 unsigned char* shm) {
;     ...
;     ATT_WAIT_BAR();
;     float sq = 0.f;
; #pragma unroll
;     for (int r = 0; r < 16; ++r) sq += o0[r] * o0[r] + o1[r] * o1[r];
;     sq += other_half(sq);
;     if (hi == 0) SS[(size_t)(rowbase + qw0 + r32) * 16 + hh] = sq;
; __global__ void __launch_bounds__(NWAVES * 64, 2) fwd_megakernel(Args args) {
;     ...
;         for (;;) {
;             if (tid == 0) qw[0] = atomicAdd(CTL, 1u);
.LBB0_405:
	s_nop 5
	v_mul_f32_e32 v2, v18, v18
	v_mul_f32_e32 v4, v19, v19
	v_fmac_f32_e32 v2, v34, v34
	v_fmac_f32_e32 v4, v35, v35
	v_add_f32_e32 v2, v2, v4
	v_mul_f32_e32 v4, v20, v20
	v_fmac_f32_e32 v4, v36, v36
	v_add_f32_e32 v2, v4, v2
	v_mul_f32_e32 v4, v21, v21
	v_fmac_f32_e32 v4, v37, v37
	v_add_f32_e32 v2, v4, v2
	v_mul_f32_e32 v4, v22, v22
	v_fmac_f32_e32 v4, v38, v38
	v_add_f32_e32 v2, v4, v2
	v_mul_f32_e32 v4, v23, v23
	v_fmac_f32_e32 v4, v39, v39
	v_add_f32_e32 v2, v4, v2
	v_mul_f32_e32 v4, v24, v24
	v_fmac_f32_e32 v4, v40, v40
	v_add_f32_e32 v2, v4, v2
	v_mul_f32_e32 v4, v25, v25
	v_fmac_f32_e32 v4, v41, v41
	v_add_f32_e32 v2, v4, v2
	v_mul_f32_e32 v4, v26, v26
	v_fmac_f32_e32 v4, v42, v42
	v_add_f32_e32 v2, v4, v2
	v_mul_f32_e32 v4, v27, v27
	v_fmac_f32_e32 v4, v43, v43
	v_add_f32_e32 v2, v4, v2
	v_mul_f32_e32 v4, v28, v28
	v_fmac_f32_e32 v4, v44, v44
	v_add_f32_e32 v2, v4, v2
	v_mul_f32_e32 v4, v29, v29
	v_fmac_f32_e32 v4, v45, v45
	v_add_f32_e32 v2, v4, v2
	v_mul_f32_e32 v4, v30, v30
	v_fmac_f32_e32 v4, v46, v46
	v_add_f32_e32 v2, v4, v2
	v_mul_f32_e32 v4, v31, v31
	v_fmac_f32_e32 v4, v47, v47
	v_add_f32_e32 v2, v4, v2
	v_mul_f32_e32 v4, v32, v32
	v_fmac_f32_e32 v4, v48, v48
	v_add_f32_e32 v2, v4, v2
	v_mul_f32_e32 v4, v33, v33
	v_fmac_f32_e32 v4, v49, v49
	s_waitcnt vmcnt(0) lgkmcnt(0)
	s_barrier
	s_mov_b64 s[98:99], exec
	v_readlane_b32 s100, v249, 10
	v_readlane_b32 s101, v249, 11
	s_nop 0
	s_and_b64 exec, s[98:99], s[100:101]
	s_cbranch_execz .Lqpf_skip2
	v_readlane_b32 s100, v249, 43
	v_readlane_b32 s101, v249, 44
	v_mov_b32_e32 v187, 1
	s_nop 3
	global_atomic_add v187, v3, v187, s[100:101] sc0
.Lqpf_skip2:
	s_mov_b64 exec, s[98:99]
	v_add_f32_e32 v4, v4, v2
	v_mov_b32_e32 v5, v4
	v_mov_b32_e32 v6, v4
	s_nop 1
	v_permlane32_swap_b32_e32 v5, v6
	s_and_saveexec_b64 s[0:1], s[8:9]
	s_cbranch_execz .LBB0_407
	v_or_b32_e32 v2, s78, v182
	v_readlane_b32 s2, v249, 41
	v_lshlrev_b64 v[8:9], 6, v[2:3]
	v_readlane_b32 s3, v249, 42
	v_cmp_eq_u32_e32 vcc, v5, v4
	s_lshl_b32 s80, s84, 2
	v_lshl_add_u64 v[8:9], s[2:3], 0, v[8:9]
	v_cndmask_b32_e32 v2, v5, v6, vcc
	v_lshl_add_u64 v[8:9], v[8:9], 0, s[80:81]
	v_add_f32_e32 v2, v4, v2
	global_store_dword v[8:9], v2, off offset:32

; __device__ __forceinline__ void fox_unit(int b, int hh, int qb, const bf16_t* Q, const bf16_t* __restrict__ K, const bf16_t* __restrict__ V, bf16_t* O, ...
;     ...
;     { const float inv = 1.0f / lacc[0];
; #pragma unroll
;         for (int r = 0; r < 16; ++r) { o0[r] *= inv; o1[r] *= inv; } }
;     float sq = 0.f;
; #pragma unroll
;     for (int r = 0; r < 16; ++r) sq += o0[r] * o0[r] + o1[r] * o1[r];
;     sq += other_half(sq);
;     if (hi == 0) SS[(size_t)(rowbase + qw0 + r32) * 16 + hh] = sq;
; __global__ void __launch_bounds__(NWAVES * 64, 2) fwd_megakernel(Args args) {
;     ...
;         for (;;) {
;             if (tid == 0) qw[0] = atomicAdd(CTL, 1u);
.LBB0_437:
	s_mov_b64 s[98:99], exec
	v_readlane_b32 s100, v249, 10
	v_readlane_b32 s101, v249, 11
	s_nop 0
	s_and_b64 exec, s[98:99], s[100:101]
	s_cbranch_execz .Lqpf_skip1
	v_readlane_b32 s100, v249, 43
	v_readlane_b32 s101, v249, 44
	v_mov_b32_e32 v187, 1
	s_nop 3
	global_atomic_add v187, v3, v187, s[100:101] sc0
.Lqpf_skip1:
	s_mov_b64 exec, s[98:99]
	s_nop 4
	v_div_scale_f32 v2, s[0:1], v66, v66, 1.0
	v_rcp_f32_e32 v4, v2
	v_div_scale_f32 v5, vcc, 1.0, v66, 1.0
	v_fma_f32 v6, -v2, v4, 1.0
	v_fmac_f32_e32 v4, v6, v4
	v_mul_f32_e32 v6, v5, v4
	v_fma_f32 v7, -v2, v6, v5
	v_fmac_f32_e32 v6, v7, v4
	v_fma_f32 v2, -v2, v6, v5
	v_div_fmas_f32 v2, v2, v4, v6
	v_div_fixup_f32 v2, v2, v66, 1.0
	v_pk_mul_f32 v[6:7], v[2:3], v[34:35] op_sel_hi:[0,1]
	v_pk_mul_f32 v[4:5], v[2:3], v[18:19] op_sel_hi:[0,1]
	v_pk_mul_f32 v[14:15], v[2:3], v[36:37] op_sel_hi:[0,1]
	v_pk_mul_f32 v[10:11], v[2:3], v[20:21] op_sel_hi:[0,1]
	v_pk_mul_f32 v[20:21], v[2:3], v[24:25] op_sel_hi:[0,1]
	v_pk_mul_f32 v[24:25], v[2:3], v[30:31] op_sel_hi:[0,1]
	v_pk_mul_f32 v[30:31], v[2:3], v[32:33] op_sel_hi:[0,1]
	v_pk_mul_f32 v[32:33], v[6:7], v[6:7]
	v_pk_mul_f32 v[12:13], v[2:3], v[38:39] op_sel_hi:[0,1]
	v_pk_fma_f32 v[32:33], v[4:5], v[4:5], v[32:33]
	v_pk_mul_f32 v[38:39], v[14:15], v[14:15]
	v_pk_mul_f32 v[8:9], v[2:3], v[22:23] op_sel_hi:[0,1]
	v_pk_mul_f32 v[22:23], v[2:3], v[40:41] op_sel_hi:[0,1]
	v_pk_mul_f32 v[18:19], v[2:3], v[42:43] op_sel_hi:[0,1]
	v_pk_mul_f32 v[16:17], v[2:3], v[26:27] op_sel_hi:[0,1]
	v_pk_mul_f32 v[34:35], v[2:3], v[44:45] op_sel_hi:[0,1]
	v_pk_mul_f32 v[26:27], v[2:3], v[28:29] op_sel_hi:[0,1]
	v_pk_mul_f32 v[28:29], v[2:3], v[46:47] op_sel_hi:[0,1]
	v_pk_mul_f32 v[36:37], v[2:3], v[48:49] op_sel_hi:[0,1]
	v_pk_fma_f32 v[38:39], v[10:11], v[10:11], v[38:39]
	v_add_f32_e32 v2, v32, v33
	v_pk_mul_f32 v[40:41], v[12:13], v[12:13]
	v_add_f32_e32 v2, v38, v2
	v_pk_fma_f32 v[40:41], v[8:9], v[8:9], v[40:41]
	v_add_f32_e32 v2, v39, v2
	v_pk_mul_f32 v[42:43], v[22:23], v[22:23]
	v_add_f32_e32 v2, v40, v2
	v_pk_fma_f32 v[42:43], v[20:21], v[20:21], v[42:43]
	v_add_f32_e32 v2, v41, v2
	v_pk_mul_f32 v[44:45], v[18:19], v[18:19]
	v_add_f32_e32 v2, v42, v2
	v_pk_fma_f32 v[44:45], v[16:17], v[16:17], v[44:45]
	v_add_f32_e32 v2, v43, v2
	v_pk_mul_f32 v[46:47], v[34:35], v[34:35]
	v_add_f32_e32 v2, v44, v2
	v_pk_fma_f32 v[46:47], v[26:27], v[26:27], v[46:47]
	v_add_f32_e32 v2, v45, v2
	v_pk_mul_f32 v[48:49], v[28:29], v[28:29]
	v_add_f32_e32 v2, v46, v2
	v_pk_fma_f32 v[48:49], v[24:25], v[24:25], v[48:49]
	v_add_f32_e32 v2, v47, v2
	v_pk_mul_f32 v[50:51], v[36:37], v[36:37]
	v_add_f32_e32 v2, v48, v2
	v_pk_fma_f32 v[50:51], v[30:31], v[30:31], v[50:51]
	v_add_f32_e32 v2, v49, v2
	v_add_f32_e32 v2, v50, v2
	v_add_f32_e32 v32, v51, v2
	v_mov_b32_e32 v33, v32
	v_mov_b32_e32 v38, v32
	s_nop 1
	v_permlane32_swap_b32_e32 v33, v38
	s_and_saveexec_b64 s[0:1], s[8:9]
	s_cbranch_execz .LBB0_356
	v_or_b32_e32 v2, s80, v182
	v_readlane_b32 s2, v249, 41
	v_lshlrev_b64 v[40:41], 6, v[2:3]
	v_readlane_b32 s3, v249, 42
	v_cmp_eq_u32_e32 vcc, v33, v32
	s_nop 0
	v_lshl_add_u64 v[40:41], s[2:3], 0, v[40:41]
	v_readlane_b32 s2, v249, 60
	s_lshl_b32 s80, s2, 2
	v_cndmask_b32_e32 v2, v33, v38, vcc
	v_lshl_add_u64 v[40:41], v[40:41], 0, s[80:81]
	v_add_f32_e32 v2, v32, v2
	global_store_dword v[40:41], v2, off
	s_branch .LBB0_356

; #define LAS __attribute__((address_space(3)))
; __global__ void __launch_bounds__(NWAVES * 64, 2) fwd_megakernel(Args args) {
;     extern __shared__ __attribute__((aligned(16))) unsigned char lds_raw[];
;     LAS unsigned char* lds = (LAS unsigned char*)lds_raw;
;     const int tid = threadIdx.x, lane = tid & 63, wave = __builtin_amdgcn_readfirstlane(tid >> 6);
	.amdhsa_kernel _Z14fwd_megakernel4Args
		.amdhsa_group_segment_fixed_size 0
		.amdhsa_private_segment_fixed_size 0
		.amdhsa_kernarg_size 384
		.amdhsa_user_sgpr_count 2
		.amdhsa_user_sgpr_dispatch_ptr 0
		.amdhsa_user_sgpr_queue_ptr 0
		.amdhsa_user_sgpr_kernarg_segment_ptr 1
		.amdhsa_user_sgpr_dispatch_id 0
		.amdhsa_user_sgpr_kernarg_preload_length 0
		.amdhsa_user_sgpr_kernarg_preload_offset 0
		.amdhsa_user_sgpr_private_segment_size 0
		.amdhsa_uses_dynamic_stack 0
		.amdhsa_enable_private_segment 0
		.amdhsa_system_sgpr_workgroup_id_x 1
		.amdhsa_system_sgpr_workgroup_id_y 0
		.amdhsa_system_sgpr_workgroup_id_z 0
		.amdhsa_system_sgpr_workgroup_info 0
		.amdhsa_system_vgpr_workitem_id 2
		.amdhsa_next_free_vgpr 250
		.amdhsa_next_free_sgpr 102
		.amdhsa_accum_offset 252
		.amdhsa_reserve_vcc 1
		.amdhsa_float_round_mode_32 0
		.amdhsa_float_round_mode_16_64 0
		.amdhsa_float_denorm_mode_32 3
		.amdhsa_float_denorm_mode_16_64 3
		.amdhsa_dx10_clamp 1
		.amdhsa_ieee_mode 1
		.amdhsa_fp16_overflow 0
		.amdhsa_tg_split 0
		.amdhsa_exception_fp_ieee_invalid_op 0
		.amdhsa_exception_fp_denorm_src 0
		.amdhsa_exception_fp_ieee_div_zero 0
		.amdhsa_exception_fp_ieee_overflow 0
		.amdhsa_exception_fp_ieee_underflow 0
		.amdhsa_exception_fp_ieee_inexact 0
		.amdhsa_exception_int_div_zero 0
	.end_amdhsa_kernel

; #define LAS __attribute__((address_space(3)))
; __global__ void __launch_bounds__(NWAVES * 64, 2) fwd_megakernel(Args args) {
;     extern __shared__ __attribute__((aligned(16))) unsigned char lds_raw[];
;     LAS unsigned char* lds = (LAS unsigned char*)lds_raw;
;     const int tid = threadIdx.x, lane = tid & 63, wave = __builtin_amdgcn_readfirstlane(tid >> 6);
amdhsa.kernels:
  - .agpr_count:     0
    .args:
      - .offset:         0
        .size:           128
        .value_kind:     by_value
      - .offset:         128
        .size:           4
        .value_kind:     hidden_block_count_x
      - .offset:         132
        .size:           4
        .value_kind:     hidden_block_count_y
      - .offset:         136
        .size:           4
        .value_kind:     hidden_block_count_z
      - .offset:         140
        .size:           2
        .value_kind:     hidden_group_size_x
      - .offset:         142
        .size:           2
        .value_kind:     hidden_group_size_y
      - .offset:         144
        .size:           2
        .value_kind:     hidden_group_size_z
      - .offset:         146
        .size:           2
        .value_kind:     hidden_remainder_x
      - .offset:         148
        .size:           2
        .value_kind:     hidden_remainder_y
      - .offset:         150
        .size:           2
        .value_kind:     hidden_remainder_z
      - .offset:         168
        .size:           8
        .value_kind:     hidden_global_offset_x
      - .offset:         176
        .size:           8
        .value_kind:     hidden_global_offset_y
      - .offset:         184
        .size:           8
        .value_kind:     hidden_global_offset_z
      - .offset:         192
        .size:           2
        .value_kind:     hidden_grid_dims
      - .offset:         216
        .size:           8
        .value_kind:     hidden_multigrid_sync_arg
      - .offset:         248
        .size:           4
        .value_kind:     hidden_dynamic_lds_size
    .group_segment_fixed_size: 0
    .kernarg_segment_align: 8
    .kernarg_segment_size: 384
    .language:       OpenCL C
    .language_version:
      - 2
      - 0
    .max_flat_workgroup_size: 512
    .name:           _Z14fwd_megakernel4Args
    .private_segment_fixed_size: 0
    .sgpr_count:     108
    .sgpr_spill_count: 65
    .symbol:         _Z14fwd_megakernel4Args.kd
    .uniform_work_group_size: 1
    .uses_dynamic_stack: false
    .vgpr_count:     250
    .vgpr_spill_count: 0
    .wavefront_size: 64
